# code placement: one 4-byte pad before the first K-loop shifts every later loop head by 4 bytes (loop heads now 4 mod 8 except FFN-up at 0 mod 8)
# baseline (speedup 1.0000x reference)
.LBB0_243:
	s_lshl_b32 s24, s12, 20
	s_and_b32 s24, s24, 0xff00000
	v_readlane_b32 s36, v248, 22
	v_readlane_b32 s37, v248, 23
	s_add_u32 s24, s36, s24
	s_addc_u32 s35, s37, 0
	s_lshr_b32 s36, s12, 13
	s_and_b32 s36, s36, 0x7ff80
	s_add_u32 s54, s24, s36
	s_addc_u32 s55, s35, 0
	s_lshl_b32 s24, s12, 12
	s_and_b32 s24, s24, 0xff00000
	v_readlane_b32 s38, v248, 24
	v_readlane_b32 s39, v248, 25
	s_add_u32 s24, s38, s24
	s_addc_u32 s35, s39, 0
	s_add_u32 s70, s24, s36
	s_addc_u32 s71, s35, 0
	s_cmp_lt_i32 s1, 1
	v_cmp_gt_i64_e64 s[72:73], s[12:13], -1
	s_cbranch_scc1 .LBB0_253
	s_and_b64 s[12:13], s[72:73], exec
	s_cselect_b32 s24, s55, s5
	s_cselect_b32 s35, s54, s4
	s_cselect_b32 s36, s71, s3
	s_cselect_b32 s37, s70, s2
	s_add_i32 s38, s1, -2
	s_add_u32 s4, s4, 0x80080
	s_addc_u32 s5, s5, 0
	s_add_u32 s39, s2, 0x100
	s_addc_u32 s40, s3, 0
	s_mov_b32 s2, 0
	v_add_u32_e32 v138, s29, v183
	ds_read_b128 v[144:147], v138
	ds_read_b128 v[148:151], v138 offset:1024
	ds_read_b128 v[152:155], v138 offset:2048
	ds_read_b128 v[156:159], v138 offset:3072
	v_add_u32_e32 v138, s34, v183
	ds_read_b128 v[160:163], v138
	ds_read_b128 v[164:167], v138 offset:1024
	ds_read_b128 v[186:189], v138 offset:2048
	ds_read_b128 v[190:193], v138 offset:3072
	s_add_i32 s41, s2, 2
	s_add_u32 s3, s4, 0xfff80080
	s_addc_u32 s12, s5, -1
	s_cmp_eq_u32 s38, s2
	s_cselect_b32 s2, s37, s39
	s_cselect_b32 s13, s24, s12
	s_cselect_b32 s12, s35, s3
	s_cselect_b32 s3, s36, s40
	s_add_i32 m0, s17, 0xc000
	ds_read_b128 v[194:197], v185
	ds_read_b128 v[198:201], v185 offset:1024
	ds_read_b128 v[202:205], v185 offset:2048
	ds_read_b128 v[208:211], v185 offset:3072
	ds_read_b128 v[212:215], v185 offset:4096
	ds_read_b128 v[216:219], v185 offset:5120
	ds_read_b128 v[220:223], v185 offset:6144
	ds_read_b128 v[224:227], v185 offset:7168
	global_load_lds_dwordx4 v140, s[4:5]
	s_add_i32 m0, s17, 0xe000
	s_nop 0
	global_load_lds_dwordx4 v142, s[4:5]
	s_waitcnt vmcnt(8)
	s_waitcnt lgkmcnt(0)
	s_barrier
	s_setprio 1
	s_waitcnt lgkmcnt(0)
	v_mfma_i32_16x16x64_i8 v[126:129], v[144:147], v[194:197], 0
	v_mfma_i32_16x16x64_i8 v[126:129], v[148:151], v[198:201], v[126:129]
	v_mfma_i32_16x16x64_i8 v[122:125], v[152:155], v[194:197], 0
	v_mfma_i32_16x16x64_i8 v[122:125], v[156:159], v[198:201], v[122:125]
	v_mfma_i32_16x16x64_i8 v[118:121], v[144:147], v[202:205], 0
	v_mfma_i32_16x16x64_i8 v[118:121], v[148:151], v[208:211], v[118:121]
	v_mfma_i32_16x16x64_i8 v[114:117], v[152:155], v[202:205], 0
	v_mfma_i32_16x16x64_i8 v[114:117], v[156:159], v[208:211], v[114:117]
	v_mfma_i32_16x16x64_i8 v[110:113], v[144:147], v[212:215], 0
	v_mfma_i32_16x16x64_i8 v[110:113], v[148:151], v[216:219], v[110:113]
	v_mfma_i32_16x16x64_i8 v[106:109], v[152:155], v[212:215], 0
	v_mfma_i32_16x16x64_i8 v[106:109], v[156:159], v[216:219], v[106:109]
	v_mfma_i32_16x16x64_i8 v[102:105], v[144:147], v[220:223], 0
	v_mfma_i32_16x16x64_i8 v[102:105], v[148:151], v[224:227], v[102:105]
	v_mfma_i32_16x16x64_i8 v[98:101], v[152:155], v[220:223], 0
	v_mfma_i32_16x16x64_i8 v[98:101], v[156:159], v[224:227], v[98:101]
	s_setprio 0
	s_setprio 1
	v_mfma_i32_16x16x64_i8 v[94:97], v[160:163], v[194:197], 0
	v_mfma_i32_16x16x64_i8 v[94:97], v[164:167], v[198:201], v[94:97]
	v_mfma_i32_16x16x64_i8 v[90:93], v[186:189], v[194:197], 0
	v_mfma_i32_16x16x64_i8 v[90:93], v[190:193], v[198:201], v[90:93]
	v_mfma_i32_16x16x64_i8 v[86:89], v[160:163], v[202:205], 0
	v_mfma_i32_16x16x64_i8 v[86:89], v[164:167], v[208:211], v[86:89]
	v_mfma_i32_16x16x64_i8 v[82:85], v[186:189], v[202:205], 0
	v_mfma_i32_16x16x64_i8 v[82:85], v[190:193], v[208:211], v[82:85]
	v_mfma_i32_16x16x64_i8 v[78:81], v[160:163], v[212:215], 0
	v_mfma_i32_16x16x64_i8 v[78:81], v[164:167], v[216:219], v[78:81]
	v_mfma_i32_16x16x64_i8 v[74:77], v[186:189], v[212:215], 0
	v_mfma_i32_16x16x64_i8 v[74:77], v[190:193], v[216:219], v[74:77]
	v_mfma_i32_16x16x64_i8 v[70:73], v[160:163], v[220:223], 0
	v_mfma_i32_16x16x64_i8 v[70:73], v[164:167], v[224:227], v[70:73]
	v_mfma_i32_16x16x64_i8 v[66:69], v[186:189], v[220:223], 0
	v_mfma_i32_16x16x64_i8 v[66:69], v[190:193], v[224:227], v[66:69]
	s_setprio 0
	s_barrier
	s_add_i32 s42, s29, s16
	s_mov_b32 m0, s42
	ds_read_b128 v[194:197], v185 offset:16384
	ds_read_b128 v[198:201], v185 offset:17408
	ds_read_b128 v[202:205], v185 offset:18432
	ds_read_b128 v[208:211], v185 offset:19456
	ds_read_b128 v[212:215], v185 offset:20480
	ds_read_b128 v[216:219], v185 offset:21504
	ds_read_b128 v[220:223], v185 offset:22528
	ds_read_b128 v[224:227], v185 offset:23552
	global_load_lds_dwordx4 v132, s[2:3]
	s_add_i32 m0, s42, 0x2000
	s_add_u32 s42, s2, 0x80000
	s_addc_u32 s43, s3, 0
	s_add_i32 s44, s34, s16
	global_load_lds_dwordx4 v136, s[2:3]
	s_mov_b32 m0, s44
	v_lshl_add_u64 v[234:235], s[12:13], 0, v[134:135]
	global_load_lds_dwordx4 v132, s[42:43]
	s_add_i32 m0, s44, 0x2000
	s_nop 0
	global_load_lds_dwordx4 v136, s[42:43]
	v_lshl_add_u64 v[232:233], s[12:13], 0, v[130:131]
	s_mov_b32 m0, s17
	s_nop 0
	global_load_lds_dwordx4 v130, s[12:13]
	s_mov_b32 m0, s18
	s_nop 0
	global_load_lds_dwordx4 v134, s[12:13]
	s_waitcnt vmcnt(8)
	s_waitcnt lgkmcnt(0)
	s_barrier
	s_setprio 1
	s_waitcnt lgkmcnt(0)
	v_mfma_i32_16x16x64_i8 v[62:65], v[144:147], v[194:197], 0
	v_mfma_i32_16x16x64_i8 v[62:65], v[148:151], v[198:201], v[62:65]
	v_mfma_i32_16x16x64_i8 v[58:61], v[152:155], v[194:197], 0
	v_mfma_i32_16x16x64_i8 v[58:61], v[156:159], v[198:201], v[58:61]
	v_mfma_i32_16x16x64_i8 v[54:57], v[144:147], v[202:205], 0
	v_mfma_i32_16x16x64_i8 v[54:57], v[148:151], v[208:211], v[54:57]
	v_mfma_i32_16x16x64_i8 v[50:53], v[152:155], v[202:205], 0
	v_mfma_i32_16x16x64_i8 v[50:53], v[156:159], v[208:211], v[50:53]
	v_mfma_i32_16x16x64_i8 v[46:49], v[144:147], v[212:215], 0
	v_mfma_i32_16x16x64_i8 v[46:49], v[148:151], v[216:219], v[46:49]
	v_mfma_i32_16x16x64_i8 v[42:45], v[152:155], v[212:215], 0
	v_mfma_i32_16x16x64_i8 v[42:45], v[156:159], v[216:219], v[42:45]
	v_mfma_i32_16x16x64_i8 v[38:41], v[144:147], v[220:223], 0
	v_mfma_i32_16x16x64_i8 v[38:41], v[148:151], v[224:227], v[38:41]
	v_mfma_i32_16x16x64_i8 v[34:37], v[152:155], v[220:223], 0
	v_mfma_i32_16x16x64_i8 v[34:37], v[156:159], v[224:227], v[34:37]
	s_setprio 0
	s_setprio 1
	v_mfma_i32_16x16x64_i8 v[30:33], v[160:163], v[194:197], 0
	v_mfma_i32_16x16x64_i8 v[30:33], v[164:167], v[198:201], v[30:33]
	v_mfma_i32_16x16x64_i8 v[26:29], v[186:189], v[194:197], 0
	v_mfma_i32_16x16x64_i8 v[26:29], v[190:193], v[198:201], v[26:29]
	v_mfma_i32_16x16x64_i8 v[22:25], v[160:163], v[202:205], 0
	v_mfma_i32_16x16x64_i8 v[22:25], v[164:167], v[208:211], v[22:25]
	v_mfma_i32_16x16x64_i8 v[18:21], v[186:189], v[202:205], 0
	v_mfma_i32_16x16x64_i8 v[18:21], v[190:193], v[208:211], v[18:21]
	v_mfma_i32_16x16x64_i8 v[14:17], v[160:163], v[212:215], 0
	v_mfma_i32_16x16x64_i8 v[14:17], v[164:167], v[216:219], v[14:17]
	v_mfma_i32_16x16x64_i8 v[10:13], v[186:189], v[212:215], 0
	v_mfma_i32_16x16x64_i8 v[10:13], v[190:193], v[216:219], v[10:13]
	v_mfma_i32_16x16x64_i8 v[6:9], v[160:163], v[220:223], 0
	v_mfma_i32_16x16x64_i8 v[6:9], v[164:167], v[224:227], v[6:9]
	v_mfma_i32_16x16x64_i8 v[2:5], v[186:189], v[220:223], 0
	v_mfma_i32_16x16x64_i8 v[2:5], v[190:193], v[224:227], v[2:5]
	s_setprio 0
	s_barrier
	s_add_i32 s42, 0, 0x18000
	v_add_u32_e32 v138, s42, v183
	s_add_i32 s43, 0, 0x1c000
	ds_read_b128 v[144:147], v138
	ds_read_b128 v[148:151], v138 offset:1024
	ds_read_b128 v[152:155], v138 offset:2048
	ds_read_b128 v[156:159], v138 offset:3072
	v_add_u32_e32 v138, s43, v183
	ds_read_b128 v[160:163], v138
	ds_read_b128 v[164:167], v138 offset:1024
	ds_read_b128 v[186:189], v138 offset:2048
	ds_read_b128 v[190:193], v138 offset:3072
	s_add_u32 s12, s12, 0x80000
	s_addc_u32 s13, s13, 0
	s_mov_b32 m0, s19
	ds_read_b128 v[194:197], v185 offset:32768
	ds_read_b128 v[198:201], v185 offset:33792
	ds_read_b128 v[202:205], v185 offset:34816
	ds_read_b128 v[208:211], v185 offset:35840
	ds_read_b128 v[212:215], v185 offset:36864
	ds_read_b128 v[216:219], v185 offset:37888
	ds_read_b128 v[220:223], v185 offset:38912
	ds_read_b128 v[224:227], v185 offset:39936
	global_load_lds_dwordx4 v130, s[12:13]
	s_mov_b32 m0, s20
	s_nop 0
	global_load_lds_dwordx4 v134, s[12:13]
	s_waitcnt vmcnt(8)
	s_waitcnt lgkmcnt(0)
	s_barrier
	s_setprio 1
	s_waitcnt lgkmcnt(0)
	v_mfma_i32_16x16x64_i8 v[126:129], v[144:147], v[194:197], v[126:129]
	v_mfma_i32_16x16x64_i8 v[126:129], v[148:151], v[198:201], v[126:129]
	v_mfma_i32_16x16x64_i8 v[122:125], v[152:155], v[194:197], v[122:125]
	v_mfma_i32_16x16x64_i8 v[122:125], v[156:159], v[198:201], v[122:125]
	v_mfma_i32_16x16x64_i8 v[118:121], v[144:147], v[202:205], v[118:121]
	v_mfma_i32_16x16x64_i8 v[118:121], v[148:151], v[208:211], v[118:121]
	v_mfma_i32_16x16x64_i8 v[114:117], v[152:155], v[202:205], v[114:117]
	v_mfma_i32_16x16x64_i8 v[114:117], v[156:159], v[208:211], v[114:117]
	v_mfma_i32_16x16x64_i8 v[110:113], v[144:147], v[212:215], v[110:113]
	v_mfma_i32_16x16x64_i8 v[110:113], v[148:151], v[216:219], v[110:113]
	v_mfma_i32_16x16x64_i8 v[106:109], v[152:155], v[212:215], v[106:109]
	v_mfma_i32_16x16x64_i8 v[106:109], v[156:159], v[216:219], v[106:109]
	v_mfma_i32_16x16x64_i8 v[102:105], v[144:147], v[220:223], v[102:105]
	v_mfma_i32_16x16x64_i8 v[102:105], v[148:151], v[224:227], v[102:105]
	v_mfma_i32_16x16x64_i8 v[98:101], v[152:155], v[220:223], v[98:101]
	v_mfma_i32_16x16x64_i8 v[98:101], v[156:159], v[224:227], v[98:101]
	s_setprio 0
	s_setprio 1
	v_mfma_i32_16x16x64_i8 v[94:97], v[160:163], v[194:197], v[94:97]
	v_mfma_i32_16x16x64_i8 v[94:97], v[164:167], v[198:201], v[94:97]
	v_mfma_i32_16x16x64_i8 v[90:93], v[186:189], v[194:197], v[90:93]
	v_mfma_i32_16x16x64_i8 v[90:93], v[190:193], v[198:201], v[90:93]
	v_mfma_i32_16x16x64_i8 v[86:89], v[160:163], v[202:205], v[86:89]
	v_mfma_i32_16x16x64_i8 v[86:89], v[164:167], v[208:211], v[86:89]
	v_mfma_i32_16x16x64_i8 v[82:85], v[186:189], v[202:205], v[82:85]
	v_mfma_i32_16x16x64_i8 v[82:85], v[190:193], v[208:211], v[82:85]
	v_mfma_i32_16x16x64_i8 v[78:81], v[160:163], v[212:215], v[78:81]
	v_mfma_i32_16x16x64_i8 v[78:81], v[164:167], v[216:219], v[78:81]
	v_mfma_i32_16x16x64_i8 v[74:77], v[186:189], v[212:215], v[74:77]
	v_mfma_i32_16x16x64_i8 v[74:77], v[190:193], v[216:219], v[74:77]
	v_mfma_i32_16x16x64_i8 v[70:73], v[160:163], v[220:223], v[70:73]
	v_mfma_i32_16x16x64_i8 v[70:73], v[164:167], v[224:227], v[70:73]
	v_mfma_i32_16x16x64_i8 v[66:69], v[186:189], v[220:223], v[66:69]
	v_mfma_i32_16x16x64_i8 v[66:69], v[190:193], v[224:227], v[66:69]
	s_setprio 0
	s_barrier
	s_add_i32 s12, s42, s16
	s_add_u32 s98, s2, s10
	s_addc_u32 s99, s3, s11
	s_mov_b32 m0, s12
	ds_read_b128 v[194:197], v185 offset:49152
	ds_read_b128 v[198:201], v185 offset:50176
	ds_read_b128 v[202:205], v185 offset:51200
	ds_read_b128 v[208:211], v185 offset:52224
	ds_read_b128 v[212:215], v185 offset:53248
	ds_read_b128 v[216:219], v185 offset:54272
	ds_read_b128 v[220:223], v185 offset:55296
	ds_read_b128 v[224:227], v185 offset:56320
	global_load_lds_dwordx4 v132, s[98:99]
	s_add_i32 m0, s12, 0x2000
	s_add_u32 s2, s2, 0x80080
	s_addc_u32 s3, s3, 0
	s_add_i32 s12, s43, s16
	global_load_lds_dwordx4 v136, s[98:99]
	s_mov_b32 m0, s12
	s_nop 0
	global_load_lds_dwordx4 v132, s[2:3]
	s_add_i32 m0, s12, 0x2000
	s_nop 0
	global_load_lds_dwordx4 v136, s[2:3]
	v_lshl_add_u64 v[228:229], v[232:233], 0, s[10:11]
	s_mov_b32 m0, s22
	s_nop 0
	global_load_lds_dwordx4 v[228:229], off
	v_lshl_add_u64 v[228:229], v[234:235], 0, s[10:11]
	s_mov_b32 m0, s23
	s_nop 0
	global_load_lds_dwordx4 v[228:229], off
	s_waitcnt vmcnt(8)
	s_waitcnt lgkmcnt(0)
	s_barrier
	s_setprio 1
	s_waitcnt lgkmcnt(0)
	v_mfma_i32_16x16x64_i8 v[62:65], v[144:147], v[194:197], v[62:65]
	v_mfma_i32_16x16x64_i8 v[62:65], v[148:151], v[198:201], v[62:65]
	v_mfma_i32_16x16x64_i8 v[58:61], v[152:155], v[194:197], v[58:61]
	v_mfma_i32_16x16x64_i8 v[58:61], v[156:159], v[198:201], v[58:61]
	v_mfma_i32_16x16x64_i8 v[54:57], v[144:147], v[202:205], v[54:57]
	v_mfma_i32_16x16x64_i8 v[54:57], v[148:151], v[208:211], v[54:57]
	v_mfma_i32_16x16x64_i8 v[50:53], v[152:155], v[202:205], v[50:53]
	v_mfma_i32_16x16x64_i8 v[50:53], v[156:159], v[208:211], v[50:53]
	v_mfma_i32_16x16x64_i8 v[46:49], v[144:147], v[212:215], v[46:49]
	v_mfma_i32_16x16x64_i8 v[46:49], v[148:151], v[216:219], v[46:49]
	v_mfma_i32_16x16x64_i8 v[42:45], v[152:155], v[212:215], v[42:45]
	v_mfma_i32_16x16x64_i8 v[42:45], v[156:159], v[216:219], v[42:45]
	v_mfma_i32_16x16x64_i8 v[38:41], v[144:147], v[220:223], v[38:41]
	v_mfma_i32_16x16x64_i8 v[38:41], v[148:151], v[224:227], v[38:41]
	v_mfma_i32_16x16x64_i8 v[34:37], v[152:155], v[220:223], v[34:37]
	v_mfma_i32_16x16x64_i8 v[34:37], v[156:159], v[224:227], v[34:37]
	s_setprio 0
	s_setprio 1
	v_mfma_i32_16x16x64_i8 v[30:33], v[160:163], v[194:197], v[30:33]
	v_mfma_i32_16x16x64_i8 v[30:33], v[164:167], v[198:201], v[30:33]
	v_mfma_i32_16x16x64_i8 v[26:29], v[186:189], v[194:197], v[26:29]
	v_mfma_i32_16x16x64_i8 v[26:29], v[190:193], v[198:201], v[26:29]
	v_mfma_i32_16x16x64_i8 v[22:25], v[160:163], v[202:205], v[22:25]
	v_mfma_i32_16x16x64_i8 v[22:25], v[164:167], v[208:211], v[22:25]
	v_mfma_i32_16x16x64_i8 v[18:21], v[186:189], v[202:205], v[18:21]
	v_mfma_i32_16x16x64_i8 v[18:21], v[190:193], v[208:211], v[18:21]
	v_mfma_i32_16x16x64_i8 v[14:17], v[160:163], v[212:215], v[14:17]
	v_mfma_i32_16x16x64_i8 v[14:17], v[164:167], v[216:219], v[14:17]
	v_mfma_i32_16x16x64_i8 v[10:13], v[186:189], v[212:215], v[10:13]
	v_mfma_i32_16x16x64_i8 v[10:13], v[190:193], v[216:219], v[10:13]
	v_mfma_i32_16x16x64_i8 v[6:9], v[160:163], v[220:223], v[6:9]
	v_mfma_i32_16x16x64_i8 v[6:9], v[164:167], v[224:227], v[6:9]
	v_mfma_i32_16x16x64_i8 v[2:5], v[186:189], v[220:223], v[2:5]
	v_mfma_i32_16x16x64_i8 v[2:5], v[190:193], v[224:227], v[2:5]
	s_setprio 0
	s_barrier
	s_add_u32 s4, s4, 0x100
	s_addc_u32 s5, s5, 0
	s_add_u32 s39, s39, 0x100
	s_addc_u32 s40, s40, 0
	s_cmp_ge_i32 s41, s1
	s_mov_b32 s2, s41
	s_cbranch_scc1 .Lkpeel_exit_0
	s_nop 0
